# ctx queue blocks swapped: RET-ctx units dispatched before A-ctx units (tail ordering)
# baseline (speedup 1.0000x reference)
.LBB0_915:
	s_or_b64 exec, exec, s[14:15]
	v_readlane_b32 s10, v254, 41
	s_waitcnt lgkmcnt(0)
	s_barrier
	v_mov_b32_e32 v0, s10
	ds_read_b32 v0, v0
	s_mov_b64 s[14:15], -1
	v_add_u32_e32 v188, s71, v238
	s_waitcnt lgkmcnt(0)
	v_readfirstlane_b32 s43, v0
	s_sub_u32 s40, s43, 0x240
	s_cmp_lt_u32 s40, 0x80
	s_cselect_b32 s10, 0x100, 0
	s_sub_u32 s40, s43, 0x340
	s_cmp_lt_u32 s40, 0x80
	s_cselect_b32 s11, 0xffffff00, 0
	s_add_i32 s43, s43, s10
	s_add_i32 s43, s43, s11
	s_cmp_gt_i32 s43, 31
	s_cbranch_scc1 .LBB0_917
	s_andn2_b64 vcc, exec, s[14:15]
	s_cbranch_vccnz .LBB0_908
	s_branch .LBB0_1097
